# P3 sample-sequence units: both FIN loads of a segment iteration issued together (second into v252..v255), one exposed latency per iteration instead of two; on top of the p3stld version
# baseline (speedup 1.0000x reference)
; __device__ __forceinline__ unsigned cvt_pk_bf16(float lo, float hi) { unsigned r; asm volatile("v_cvt_pk_bf16_f32 %0, %1, %2" : "=v"(r) : "v"(lo), "v"(hi)); return r; }
; __device__ __forceinline__ u32x4 fp8x8_to_bf16x8(unsigned u0, unsigned u1) {
;     const f32x2c a = __builtin_amdgcn_cvt_pk_f32_fp8((int)u0, false), b = __builtin_amdgcn_cvt_pk_f32_fp8((int)u0, true);
;     const f32x2c c = __builtin_amdgcn_cvt_pk_f32_fp8((int)u1, false), d = __builtin_amdgcn_cvt_pk_f32_fp8((int)u1, true);
;     u32x4 o; o.x = cvt_pk_bf16(a.x, a.y); o.y = cvt_pk_bf16(b.x, b.y); o.z = cvt_pk_bf16(c.x, c.y); o.w = cvt_pk_bf16(d.x, d.y); return o;
; __device__ __forceinline__ void ret_phase(const Params& P, LAS unsigned char* lds, int tid, int lane, int wave, int bid, int G) {
;     ...
; #pragma unroll
;                 for (int jj = 0; jj < 2; ++jj) { const u32x4 rf = *(const u32x4*)(F + 16 * (tid + 512 * jj)); const u32x4 f0 = fp8x8_to_bf16x8(rf.x, rf.y), f1 = fp8x8_to_bf16x8(rf.z, rf.w);
;                     ST_FMA(sfr[2 * jj], f0, wgt); ST_FMA(sfr[2 * jj + 1], f1, wgt); }
;                 wgt *= df32; }
.LBB0_387:
	s_lshl_b64 s[0:1], s[18:19], 16
	v_lshlrev_b32_e32 v144, 16, v70
	v_and_b32_e32 v145, 0xffff0000, v70
	v_lshlrev_b32_e32 v146, 16, v71
	v_and_b32_e32 v147, 0xffff0000, v71
	v_lshl_add_u64 v[70:71], v[120:121], 0, s[0:1]
	v_lshlrev_b32_e32 v119, 16, v66
	v_and_b32_e32 v135, 0xffff0000, v66
	v_lshlrev_b32_e32 v138, 16, v67
	v_and_b32_e32 v139, 0xffff0000, v67
	v_lshlrev_b32_e32 v140, 16, v68
	v_and_b32_e32 v141, 0xffff0000, v68
	v_lshlrev_b32_e32 v142, 16, v69
	v_and_b32_e32 v143, 0xffff0000, v69
	global_load_dwordx4 v[66:69], v[70:71], off
	v_add_co_u32_e32 v100, vcc, s49, v70
	v_lshlrev_b32_e32 v148, 16, v72
	v_and_b32_e32 v149, 0xffff0000, v72
	v_lshlrev_b32_e32 v150, 16, v73
	v_and_b32_e32 v151, 0xffff0000, v73
	v_addc_co_u32_e32 v101, vcc, 0, v71, vcc
	global_load_dwordx4 v[252:255], v[100:101], off
	s_add_i32 s18, s18, -4
	s_add_i32 s35, s35, -1
	s_cmp_lt_u32 s35, 2
	s_waitcnt vmcnt(1)
	v_cvt_pk_f32_fp8_e32 v[70:71], v66
	v_cvt_pk_f32_fp8_sdwa v[72:73], v66 src0_sel:WORD_1
	v_cvt_pk_f32_fp8_e32 v[102:103], v67
	v_cvt_pk_f32_fp8_sdwa v[66:67], v67 src0_sel:WORD_1
	v_cvt_pk_f32_fp8_e32 v[122:123], v68
	v_cvt_pk_f32_fp8_sdwa v[124:125], v68 src0_sel:WORD_1
	v_cvt_pk_f32_fp8_e32 v[136:137], v69
	v_cvt_pk_f32_fp8_sdwa v[68:69], v69 src0_sel:WORD_1
	v_cvt_pk_bf16_f32 v70, v70, v71
	v_cvt_pk_bf16_f32 v71, v72, v73
	v_cvt_pk_bf16_f32 v72, v102, v103
	v_cvt_pk_bf16_f32 v66, v66, v67
	v_cvt_pk_bf16_f32 v67, v122, v123
	v_cvt_pk_bf16_f32 v73, v124, v125
	v_cvt_pk_bf16_f32 v102, v136, v137
	v_cvt_pk_bf16_f32 v68, v68, v69
	s_nop 0
	v_lshlrev_b32_e32 v69, 16, v70
	v_and_b32_e32 v70, 0xffff0000, v70
	v_lshlrev_b32_e32 v103, 16, v71
	v_and_b32_e32 v71, 0xffff0000, v71
	v_lshlrev_b32_e32 v122, 16, v72
	v_and_b32_e32 v72, 0xffff0000, v72
	v_lshlrev_b32_e32 v123, 16, v66
	v_and_b32_e32 v66, 0xffff0000, v66
	v_lshlrev_b32_e32 v124, 16, v67
	v_and_b32_e32 v67, 0xffff0000, v67
	v_lshlrev_b32_e32 v125, 16, v73
	v_and_b32_e32 v73, 0xffff0000, v73
	v_lshlrev_b32_e32 v136, 16, v102
	v_and_b32_e32 v102, 0xffff0000, v102
	v_lshlrev_b32_e32 v137, 16, v68
	v_and_b32_e32 v68, 0xffff0000, v68
	v_fmac_f32_e32 v119, v99, v69
	v_fmac_f32_e32 v135, v99, v70
	v_fmac_f32_e32 v138, v99, v103
	v_fmac_f32_e32 v139, v99, v71
	v_fmac_f32_e32 v140, v99, v122
	v_fmac_f32_e32 v141, v99, v72
	v_fmac_f32_e32 v142, v99, v123
	v_fmac_f32_e32 v143, v99, v66
	v_fmac_f32_e32 v144, v99, v124
	v_fmac_f32_e32 v145, v99, v67
	v_fmac_f32_e32 v146, v99, v125
	v_fmac_f32_e32 v147, v99, v73
	v_fmac_f32_e32 v148, v99, v136
	v_fmac_f32_e32 v149, v99, v102
	v_fmac_f32_e32 v150, v99, v137
	v_fmac_f32_e32 v151, v99, v68
	v_cvt_pk_bf16_f32 v66, v119, v135
	v_cvt_pk_bf16_f32 v67, v138, v139
	v_cvt_pk_bf16_f32 v68, v140, v141
	v_cvt_pk_bf16_f32 v69, v142, v143
	v_cvt_pk_bf16_f32 v70, v144, v145
	v_cvt_pk_bf16_f32 v71, v146, v147
	v_cvt_pk_bf16_f32 v72, v148, v149
	v_cvt_pk_bf16_f32 v73, v150, v151
	s_waitcnt vmcnt(0)
	v_mov_b32_e32 v100, v252
	v_mov_b32_e32 v101, v253
	v_mov_b32_e32 v102, v254
	v_mov_b32_e32 v103, v255
	v_lshlrev_b32_e32 v119, 16, v82
	v_and_b32_e32 v135, 0xffff0000, v82
	v_lshlrev_b32_e32 v136, 16, v83
	v_and_b32_e32 v137, 0xffff0000, v83
	v_lshlrev_b32_e32 v138, 16, v84
	v_and_b32_e32 v139, 0xffff0000, v84
	v_lshlrev_b32_e32 v140, 16, v85
	v_and_b32_e32 v141, 0xffff0000, v85
	v_lshlrev_b32_e32 v142, 16, v86
	v_and_b32_e32 v143, 0xffff0000, v86
	v_lshlrev_b32_e32 v144, 16, v87
	v_and_b32_e32 v145, 0xffff0000, v87
	v_lshlrev_b32_e32 v146, 16, v88
	v_and_b32_e32 v147, 0xffff0000, v88
	v_lshlrev_b32_e32 v148, 16, v89
	v_and_b32_e32 v149, 0xffff0000, v89
	s_waitcnt vmcnt(0)
	v_cvt_pk_f32_fp8_e32 v[82:83], v100
	v_cvt_pk_f32_fp8_sdwa v[84:85], v100 src0_sel:WORD_1
	v_cvt_pk_f32_fp8_e32 v[86:87], v101
	v_cvt_pk_f32_fp8_sdwa v[88:89], v101 src0_sel:WORD_1
	v_cvt_pk_f32_fp8_e32 v[100:101], v102
	v_cvt_pk_f32_fp8_sdwa v[122:123], v102 src0_sel:WORD_1
	v_cvt_pk_f32_fp8_e32 v[124:125], v103
	v_cvt_pk_f32_fp8_sdwa v[102:103], v103 src0_sel:WORD_1
	v_cvt_pk_bf16_f32 v82, v82, v83
	v_cvt_pk_bf16_f32 v83, v84, v85
	v_cvt_pk_bf16_f32 v84, v86, v87
	v_cvt_pk_bf16_f32 v85, v88, v89
	v_cvt_pk_bf16_f32 v86, v100, v101
	v_cvt_pk_bf16_f32 v87, v122, v123
	v_cvt_pk_bf16_f32 v88, v124, v125
	v_cvt_pk_bf16_f32 v89, v102, v103
	s_nop 0
	v_lshlrev_b32_e32 v100, 16, v82
	v_and_b32_e32 v82, 0xffff0000, v82
	v_lshlrev_b32_e32 v101, 16, v83
	v_and_b32_e32 v83, 0xffff0000, v83
	v_lshlrev_b32_e32 v102, 16, v84
	v_and_b32_e32 v84, 0xffff0000, v84
	v_lshlrev_b32_e32 v103, 16, v85
	v_and_b32_e32 v85, 0xffff0000, v85
	v_lshlrev_b32_e32 v122, 16, v86
	v_and_b32_e32 v86, 0xffff0000, v86
	v_lshlrev_b32_e32 v123, 16, v87
	v_and_b32_e32 v87, 0xffff0000, v87
	v_lshlrev_b32_e32 v124, 16, v88
	v_and_b32_e32 v88, 0xffff0000, v88
	v_lshlrev_b32_e32 v125, 16, v89
	v_and_b32_e32 v89, 0xffff0000, v89
	v_fmac_f32_e32 v119, v99, v100
	v_fmac_f32_e32 v135, v99, v82
	v_fmac_f32_e32 v136, v99, v101
	v_fmac_f32_e32 v137, v99, v83
	v_fmac_f32_e32 v138, v99, v102
	v_fmac_f32_e32 v139, v99, v84
	v_fmac_f32_e32 v140, v99, v103
	v_fmac_f32_e32 v141, v99, v85
	v_fmac_f32_e32 v142, v99, v122
	v_fmac_f32_e32 v143, v99, v86
	v_fmac_f32_e32 v144, v99, v123
	v_fmac_f32_e32 v145, v99, v87
	v_fmac_f32_e32 v146, v99, v124
	v_fmac_f32_e32 v147, v99, v88
	v_fmac_f32_e32 v148, v99, v125
	v_fmac_f32_e32 v149, v99, v89
	v_mul_f32_e32 v99, v98, v99
	v_cvt_pk_bf16_f32 v82, v119, v135
	v_cvt_pk_bf16_f32 v83, v136, v137
	v_cvt_pk_bf16_f32 v84, v138, v139
	v_cvt_pk_bf16_f32 v85, v140, v141
	v_cvt_pk_bf16_f32 v86, v142, v143
	v_cvt_pk_bf16_f32 v87, v144, v145
	v_cvt_pk_bf16_f32 v88, v146, v147
	v_cvt_pk_bf16_f32 v89, v148, v149
	s_cbranch_scc0 .LBB0_387

; __device__ __forceinline__ unsigned cvt_pk_bf16(float lo, float hi) { unsigned r; asm volatile("v_cvt_pk_bf16_f32 %0, %1, %2" : "=v"(r) : "v"(lo), "v"(hi)); return r; }
; __device__ __forceinline__ u32x4 fp8x8_to_bf16x8(unsigned u0, unsigned u1) {
;     const f32x2c a = __builtin_amdgcn_cvt_pk_f32_fp8((int)u0, false), b = __builtin_amdgcn_cvt_pk_f32_fp8((int)u0, true);
;     const f32x2c c = __builtin_amdgcn_cvt_pk_f32_fp8((int)u1, false), d = __builtin_amdgcn_cvt_pk_f32_fp8((int)u1, true);
;     u32x4 o; o.x = cvt_pk_bf16(a.x, a.y); o.y = cvt_pk_bf16(b.x, b.y); o.z = cvt_pk_bf16(c.x, c.y); o.w = cvt_pk_bf16(d.x, d.y); return o;
; __device__ __forceinline__ void ret_phase(const Params& P, LAS unsigned char* lds, int tid, int lane, int wave, int bid, int G) {
;     ...
;             for (int i2 = k + 1; i2 < 4; ++i2) { const unsigned char* F = (const unsigned char*)(FIN + ((size_t)((16 + i2) * 4 + h) * 2 + 1) * 16384);
; #pragma unroll
;                 for (int jj = 0; jj < 2; ++jj) { const u32x4 rf = *(const u32x4*)(F + 16 * (tid + 512 * jj)); const u32x4 f0 = fp8x8_to_bf16x8(rf.x, rf.y), f1 = fp8x8_to_bf16x8(rf.z, rf.w);
;                     ST_FMA(sbr[2 * jj], f0, wgt); ST_FMA(sbr[2 * jj + 1], f1, wgt); }
;                 wgt *= db32; }
.LBB0_390:
	s_lshl_b64 s[0:1], s[18:19], 1
	s_add_u32 s0, s16, s0
	s_addc_u32 s1, s17, s1
	v_lshlrev_b32_e32 v119, 16, v74
	v_and_b32_e32 v135, 0xffff0000, v74
	v_lshlrev_b32_e32 v138, 16, v75
	v_and_b32_e32 v139, 0xffff0000, v75
	v_lshl_add_u64 v[74:75], s[0:1], 0, v[116:117]
	v_lshlrev_b32_e32 v140, 16, v76
	v_and_b32_e32 v141, 0xffff0000, v76
	v_add_co_u32_e32 v76, vcc, s47, v74
	v_lshlrev_b32_e32 v142, 16, v77
	v_and_b32_e32 v143, 0xffff0000, v77
	v_addc_co_u32_e32 v77, vcc, 0, v75, vcc
	v_add_co_u32_e32 v100, vcc, s50, v74
	v_lshlrev_b32_e32 v144, 16, v78
	s_nop 0
	v_addc_co_u32_e32 v101, vcc, 0, v75, vcc
	global_load_dwordx4 v[74:77], v[76:77], off
	global_load_dwordx4 v[252:255], v[100:101], off
	v_and_b32_e32 v145, 0xffff0000, v78
	v_lshlrev_b32_e32 v146, 16, v79
	v_and_b32_e32 v147, 0xffff0000, v79
	v_lshlrev_b32_e32 v148, 16, v80
	v_and_b32_e32 v149, 0xffff0000, v80
	v_lshlrev_b32_e32 v150, 16, v81
	v_and_b32_e32 v151, 0xffff0000, v81
	s_add_i32 s18, s18, 0x20000
	s_add_i32 s4, s4, 1
	s_cmp_lt_u32 s4, 2
	s_waitcnt vmcnt(1)
	v_cvt_pk_f32_fp8_e32 v[78:79], v74
	v_cvt_pk_f32_fp8_sdwa v[80:81], v74 src0_sel:WORD_1
	v_cvt_pk_f32_fp8_e32 v[102:103], v75
	v_cvt_pk_f32_fp8_sdwa v[74:75], v75 src0_sel:WORD_1
	v_cvt_pk_f32_fp8_e32 v[122:123], v76
	v_cvt_pk_f32_fp8_sdwa v[124:125], v76 src0_sel:WORD_1
	v_cvt_pk_f32_fp8_e32 v[136:137], v77
	v_cvt_pk_f32_fp8_sdwa v[76:77], v77 src0_sel:WORD_1
	v_cvt_pk_bf16_f32 v78, v78, v79
	v_cvt_pk_bf16_f32 v79, v80, v81
	v_cvt_pk_bf16_f32 v80, v102, v103
	v_cvt_pk_bf16_f32 v74, v74, v75
	v_cvt_pk_bf16_f32 v75, v122, v123
	v_cvt_pk_bf16_f32 v81, v124, v125
	v_cvt_pk_bf16_f32 v102, v136, v137
	v_cvt_pk_bf16_f32 v76, v76, v77
	s_nop 0
	v_lshlrev_b32_e32 v77, 16, v78
	v_and_b32_e32 v78, 0xffff0000, v78
	v_lshlrev_b32_e32 v103, 16, v79
	v_and_b32_e32 v79, 0xffff0000, v79
	v_lshlrev_b32_e32 v122, 16, v80
	v_and_b32_e32 v80, 0xffff0000, v80
	v_lshlrev_b32_e32 v123, 16, v74
	v_and_b32_e32 v74, 0xffff0000, v74
	v_lshlrev_b32_e32 v124, 16, v75
	v_and_b32_e32 v75, 0xffff0000, v75
	v_lshlrev_b32_e32 v125, 16, v81
	v_and_b32_e32 v81, 0xffff0000, v81
	v_lshlrev_b32_e32 v136, 16, v102
	v_and_b32_e32 v102, 0xffff0000, v102
	v_lshlrev_b32_e32 v137, 16, v76
	v_and_b32_e32 v76, 0xffff0000, v76
	v_fmac_f32_e32 v119, v98, v77
	v_fmac_f32_e32 v135, v98, v78
	v_fmac_f32_e32 v138, v98, v103
	v_fmac_f32_e32 v139, v98, v79
	v_fmac_f32_e32 v140, v98, v122
	v_fmac_f32_e32 v141, v98, v80
	v_fmac_f32_e32 v142, v98, v123
	v_fmac_f32_e32 v143, v98, v74
	v_fmac_f32_e32 v144, v98, v124
	v_fmac_f32_e32 v145, v98, v75
	v_fmac_f32_e32 v146, v98, v125
	v_fmac_f32_e32 v147, v98, v81
	v_fmac_f32_e32 v148, v98, v136
	v_fmac_f32_e32 v149, v98, v102
	v_fmac_f32_e32 v150, v98, v137
	v_fmac_f32_e32 v151, v98, v76
	v_cvt_pk_bf16_f32 v74, v119, v135
	v_cvt_pk_bf16_f32 v75, v138, v139
	v_cvt_pk_bf16_f32 v76, v140, v141
	v_cvt_pk_bf16_f32 v77, v142, v143
	v_cvt_pk_bf16_f32 v78, v144, v145
	v_cvt_pk_bf16_f32 v79, v146, v147
	v_cvt_pk_bf16_f32 v80, v148, v149
	v_cvt_pk_bf16_f32 v81, v150, v151
	s_waitcnt vmcnt(0)
	v_mov_b32_e32 v100, v252
	v_mov_b32_e32 v101, v253
	v_mov_b32_e32 v102, v254
	v_mov_b32_e32 v103, v255
	v_lshlrev_b32_e32 v119, 16, v90
	v_and_b32_e32 v135, 0xffff0000, v90
	v_lshlrev_b32_e32 v136, 16, v91
	v_and_b32_e32 v137, 0xffff0000, v91
	v_lshlrev_b32_e32 v138, 16, v92
	v_and_b32_e32 v139, 0xffff0000, v92
	v_lshlrev_b32_e32 v140, 16, v93
	v_and_b32_e32 v141, 0xffff0000, v93
	v_lshlrev_b32_e32 v142, 16, v94
	v_and_b32_e32 v143, 0xffff0000, v94
	v_lshlrev_b32_e32 v144, 16, v95
	v_and_b32_e32 v145, 0xffff0000, v95
	v_lshlrev_b32_e32 v146, 16, v96
	v_and_b32_e32 v147, 0xffff0000, v96
	v_lshlrev_b32_e32 v148, 16, v97
	v_and_b32_e32 v149, 0xffff0000, v97
	s_waitcnt vmcnt(0)
	v_cvt_pk_f32_fp8_e32 v[90:91], v100
	v_cvt_pk_f32_fp8_sdwa v[92:93], v100 src0_sel:WORD_1
	v_cvt_pk_f32_fp8_e32 v[94:95], v101
	v_cvt_pk_f32_fp8_sdwa v[96:97], v101 src0_sel:WORD_1
	v_cvt_pk_f32_fp8_e32 v[100:101], v102
	v_cvt_pk_f32_fp8_sdwa v[122:123], v102 src0_sel:WORD_1
	v_cvt_pk_f32_fp8_e32 v[124:125], v103
	v_cvt_pk_f32_fp8_sdwa v[102:103], v103 src0_sel:WORD_1
	v_cvt_pk_bf16_f32 v90, v90, v91
	v_cvt_pk_bf16_f32 v91, v92, v93
	v_cvt_pk_bf16_f32 v92, v94, v95
	v_cvt_pk_bf16_f32 v93, v96, v97
	v_cvt_pk_bf16_f32 v94, v100, v101
	v_cvt_pk_bf16_f32 v95, v122, v123
	v_cvt_pk_bf16_f32 v96, v124, v125
	v_cvt_pk_bf16_f32 v97, v102, v103
	s_nop 0
	v_lshlrev_b32_e32 v100, 16, v90
	v_and_b32_e32 v90, 0xffff0000, v90
	v_lshlrev_b32_e32 v101, 16, v91
	v_and_b32_e32 v91, 0xffff0000, v91
	v_lshlrev_b32_e32 v102, 16, v92
	v_and_b32_e32 v92, 0xffff0000, v92
	v_lshlrev_b32_e32 v103, 16, v93
	v_and_b32_e32 v93, 0xffff0000, v93
	v_lshlrev_b32_e32 v122, 16, v94
	v_and_b32_e32 v94, 0xffff0000, v94
	v_lshlrev_b32_e32 v123, 16, v95
	v_and_b32_e32 v95, 0xffff0000, v95
	v_lshlrev_b32_e32 v124, 16, v96
	v_and_b32_e32 v96, 0xffff0000, v96
	v_lshlrev_b32_e32 v125, 16, v97
	v_and_b32_e32 v97, 0xffff0000, v97
	v_fmac_f32_e32 v119, v98, v100
	v_fmac_f32_e32 v135, v98, v90
	v_fmac_f32_e32 v136, v98, v101
	v_fmac_f32_e32 v137, v98, v91
	v_fmac_f32_e32 v138, v98, v102
	v_fmac_f32_e32 v139, v98, v92
	v_fmac_f32_e32 v140, v98, v103
	v_fmac_f32_e32 v141, v98, v93
	v_fmac_f32_e32 v142, v98, v122
	v_fmac_f32_e32 v143, v98, v94
	v_fmac_f32_e32 v144, v98, v123
	v_fmac_f32_e32 v145, v98, v95
	v_fmac_f32_e32 v146, v98, v124
	v_fmac_f32_e32 v147, v98, v96
	v_fmac_f32_e32 v148, v98, v125
	v_fmac_f32_e32 v149, v98, v97
	v_mul_f32_e32 v98, v99, v98
	v_cvt_pk_bf16_f32 v90, v119, v135
	v_cvt_pk_bf16_f32 v91, v136, v137
	v_cvt_pk_bf16_f32 v92, v138, v139
	v_cvt_pk_bf16_f32 v93, v140, v141
	v_cvt_pk_bf16_f32 v94, v142, v143
	v_cvt_pk_bf16_f32 v95, v144, v145
	v_cvt_pk_bf16_f32 v96, v146, v147
	v_cvt_pk_bf16_f32 v97, v148, v149
	s_cbranch_scc1 .LBB0_390
